# attention: fused path issues QK fragment reads first and interleaves the next-tile LDS-DMA instructions with the QK MFMAs
# speedup vs baseline: 1.0100x; 1.0100x over previous
; #define LAS __attribute__((address_space(3)))
; DI void gload_lds16(const void* g, LAS char* l) { __builtin_amdgcn_global_load_lds((const unsigned*)g, (LAS unsigned*)l, 16, 0, 0); }
; DI void phase_attn(const Params& p, int l, LAS char* lds) {
;     ...
;         auto issue = [&](int stage, int kt) {
;             LAS char* base = lds + stage * 20480 + w * 1024;
; #pragma unroll
;             for (int j = 0; j < 3; ++j) {
;                 int tk = kt * 64 + krow_[j]; tk = (tk < LSEQ) ? tk : LSEQ - 1;
;                 const bf16_t* src = (kc_[j] < 8) ? Knb + (size_t)tk * 512 + kc_[j] * 8 : Krb + (size_t)tk * 32 + (kc_[j] - 8) * 8;
;                 gload_lds16(src, base + j * 4096);
;             }
; #pragma unroll
;             for (int j = 0; j < 2; ++j) gload_lds16(Vtb + (size_t)vrow_[j] * LP + kt * 64 + vc_[j] * 8, base + 12288 + j * 4096);
;         };
;     ...
;         for (int kt = 0; kt < nkt; ++kt) {
;             asm volatile("s_waitcnt vmcnt(0)" ::: "memory");
;             __syncthreads();
;             if (kt + 1 < nkt) issue((kt + 1) & 1, kt + 1);
;             if (kt * 64 > q0w + 31) continue;
;             LAS char* st = lds + (kt & 1) * 20480;
;             f32x16 s0, s1;
; #pragma unroll
;             for (int r = 0; r < 16; ++r) { s0[r] = 0.f; s1[r] = 0.f; }
; #pragma unroll
;             for (int s = 0; s < 6; ++s) {
;                 const int pos = ((2 * s + hh) ^ ksw) << 4;
;                 const bf16x8 k0 = *(LAS bf16x8*)(st + qi * 192 + pos);
;                 const bf16x8 k1 = *(LAS bf16x8*)(st + (qi + 32) * 192 + pos);
;                 s0 = __builtin_amdgcn_mfma_f32_32x32x16_bf16(k0, qf[s], s0, 0, 0, 0);
;                 s1 = __builtin_amdgcn_mfma_f32_32x32x16_bf16(k1, qf[s], s1, 0, 0, 0);
;             }
.LBB0_284:
	s_waitcnt vmcnt(0)
	s_add_i32 s33, s4, 1
	s_cmp_ge_u32 s33, s1
	s_waitcnt lgkmcnt(0)
	s_barrier
	s_cbranch_scc1 .LBB0_287
	s_cmp_eq_u32 s33, 64
	s_cbranch_scc1 .Lat_slow
	v_cmp_le_i32_e32 vcc, s23, v121
	s_bitcmp1_b32 s33, 0
	s_cselect_b32 s5, 0x5000, 0
	s_add_u32 s5, s5, s100
	s_add_i32 s34, s23, 64
	s_lshl_b64 s[6:7], s[34:35], 1
	s_and_saveexec_b64 s[48:49], vcc
	s_cbranch_execz .Lat_fnc
	s_bitcmp1_b32 s4, 0
	s_cselect_b32 s34, 0x5000, 0
	s_cbranch_scc1 .Lfq_s1
	ds_read_b128 v[34:37], v188 offset:0
	ds_read_b128 v[50:53], v188 offset:6144
	ds_read_b128 v[184:187], v189 offset:0
	ds_read_b128 a[0:3], v189 offset:6144
	ds_read_b128 v[204:207], v190 offset:0
	ds_read_b128 a[4:7], v190 offset:6144
	ds_read_b128 v[220:223], v191 offset:0
	ds_read_b128 a[8:11], v191 offset:6144
	ds_read_b128 v[224:227], v192 offset:0
	ds_read_b128 a[12:15], v192 offset:6144
	ds_read_b128 a[16:19], v193 offset:0
	ds_read_b128 a[20:23], v193 offset:6144
	s_add_i32 s4, s23, 63
	v_cmp_gt_i32_e32 vcc, s4, v123
	s_mov_b32 m0, s5
	s_waitcnt lgkmcnt(10)
	v_mfma_f32_32x32x16_bf16 v[34:49], v[34:37], v[66:69], 0
	global_load_lds_dwordx4 v[208:209], off
	v_mfma_f32_32x32x16_bf16 v[50:65], v[50:53], v[66:69], 0
	s_add_u32 m0, s5, 0x1000
	v_lshl_add_u64 v[208:209], v[208:209], 0, v[214:215]
	s_waitcnt lgkmcnt(8)
	v_mfma_f32_32x32x16_bf16 v[34:49], v[184:187], v[70:73], v[34:49]
	global_load_lds_dwordx4 v[210:211], off
	v_mfma_f32_32x32x16_bf16 v[50:65], a[0:3], v[70:73], v[50:65]
	s_add_u32 m0, s5, 0x2000
	v_lshl_add_u64 v[210:211], v[210:211], 0, v[216:217]
	s_waitcnt lgkmcnt(6)
	v_mfma_f32_32x32x16_bf16 v[34:49], v[204:207], v[74:77], v[34:49]
	global_load_lds_dwordx4 v[212:213], off
	v_mfma_f32_32x32x16_bf16 v[50:65], a[4:7], v[74:77], v[50:65]
	s_add_u32 m0, s5, 0x3000
	v_lshl_add_u64 v[212:213], v[212:213], 0, v[218:219]
	v_lshl_add_u64 v[202:203], v[124:125], 0, s[6:7]
	s_waitcnt lgkmcnt(4)
	v_mfma_f32_32x32x16_bf16 v[34:49], v[220:223], v[78:81], v[34:49]
	global_load_lds_dwordx4 v[202:203], off
	v_mfma_f32_32x32x16_bf16 v[50:65], a[8:11], v[78:81], v[50:65]
	s_add_u32 m0, s5, 0x4000
	v_lshl_add_u64 v[202:203], v[126:127], 0, s[6:7]
	s_waitcnt lgkmcnt(2)
	v_mfma_f32_32x32x16_bf16 v[34:49], v[224:227], v[82:85], v[34:49]
	global_load_lds_dwordx4 v[202:203], off
	v_mfma_f32_32x32x16_bf16 v[50:65], a[12:15], v[82:85], v[50:65]
	s_waitcnt lgkmcnt(0)
	v_mfma_f32_32x32x16_bf16 v[34:49], a[16:19], v[86:89], v[34:49]
	v_mfma_f32_32x32x16_bf16 v[50:65], a[20:23], v[86:89], v[50:65]
	s_nop 1
	s_branch .Lqk_done
.Lfq_s1:
	ds_read_b128 v[34:37], v188 offset:20480
	ds_read_b128 v[50:53], v188 offset:26624
	ds_read_b128 v[184:187], v189 offset:20480
	ds_read_b128 a[0:3], v189 offset:26624
	ds_read_b128 v[204:207], v190 offset:20480
	ds_read_b128 a[4:7], v190 offset:26624
	ds_read_b128 v[220:223], v191 offset:20480
	ds_read_b128 a[8:11], v191 offset:26624
	ds_read_b128 v[224:227], v192 offset:20480
	ds_read_b128 a[12:15], v192 offset:26624
	ds_read_b128 a[16:19], v193 offset:20480
	ds_read_b128 a[20:23], v193 offset:26624
	s_add_i32 s4, s23, 63
	v_cmp_gt_i32_e32 vcc, s4, v123
	s_mov_b32 m0, s5
	s_waitcnt lgkmcnt(10)
	v_mfma_f32_32x32x16_bf16 v[34:49], v[34:37], v[66:69], 0
	global_load_lds_dwordx4 v[208:209], off
	v_mfma_f32_32x32x16_bf16 v[50:65], v[50:53], v[66:69], 0
	s_add_u32 m0, s5, 0x1000
	v_lshl_add_u64 v[208:209], v[208:209], 0, v[214:215]
	s_waitcnt lgkmcnt(8)
	v_mfma_f32_32x32x16_bf16 v[34:49], v[184:187], v[70:73], v[34:49]
	global_load_lds_dwordx4 v[210:211], off
	v_mfma_f32_32x32x16_bf16 v[50:65], a[0:3], v[70:73], v[50:65]
	s_add_u32 m0, s5, 0x2000
	v_lshl_add_u64 v[210:211], v[210:211], 0, v[216:217]
	s_waitcnt lgkmcnt(6)
	v_mfma_f32_32x32x16_bf16 v[34:49], v[204:207], v[74:77], v[34:49]
	global_load_lds_dwordx4 v[212:213], off
	v_mfma_f32_32x32x16_bf16 v[50:65], a[4:7], v[74:77], v[50:65]
	s_add_u32 m0, s5, 0x3000
	v_lshl_add_u64 v[212:213], v[212:213], 0, v[218:219]
	v_lshl_add_u64 v[202:203], v[124:125], 0, s[6:7]
	s_waitcnt lgkmcnt(4)
	v_mfma_f32_32x32x16_bf16 v[34:49], v[220:223], v[78:81], v[34:49]
	global_load_lds_dwordx4 v[202:203], off
	v_mfma_f32_32x32x16_bf16 v[50:65], a[8:11], v[78:81], v[50:65]
	s_add_u32 m0, s5, 0x4000
	v_lshl_add_u64 v[202:203], v[126:127], 0, s[6:7]
	s_waitcnt lgkmcnt(2)
	v_mfma_f32_32x32x16_bf16 v[34:49], v[224:227], v[82:85], v[34:49]
	global_load_lds_dwordx4 v[202:203], off
	v_mfma_f32_32x32x16_bf16 v[50:65], a[12:15], v[82:85], v[50:65]
	s_waitcnt lgkmcnt(0)
	v_mfma_f32_32x32x16_bf16 v[34:49], a[16:19], v[86:89], v[34:49]
	v_mfma_f32_32x32x16_bf16 v[50:65], a[20:23], v[86:89], v[50:65]
	s_nop 1
	s_branch .Lqk_done
.Lat_fnc:
	s_or_b64 exec, exec, s[48:49]
	s_bitcmp1_b32 s33, 0
	s_cselect_b32 s5, 0x5000, 0
	s_add_u32 s5, s5, s100
	s_mov_b32 m0, s5
	s_add_i32 s34, s23, 64
	global_load_lds_dwordx4 v[208:209], off
	s_add_u32 m0, s5, 0x1000
	v_lshl_add_u64 v[208:209], v[208:209], 0, v[214:215]
	global_load_lds_dwordx4 v[210:211], off
	s_add_u32 m0, s5, 0x2000
	v_lshl_add_u64 v[210:211], v[210:211], 0, v[216:217]
	global_load_lds_dwordx4 v[212:213], off
	s_lshl_b64 s[6:7], s[34:35], 1
	v_lshl_add_u64 v[212:213], v[212:213], 0, v[218:219]
	s_add_u32 m0, s5, 0x3000
	v_lshl_add_u64 v[34:35], v[124:125], 0, s[6:7]
	global_load_lds_dwordx4 v[34:35], off
	s_add_u32 m0, s5, 0x4000
	v_lshl_add_u64 v[34:35], v[126:127], 0, s[6:7]
	global_load_lds_dwordx4 v[34:35], off
	s_branch .Lat_issued
